# topk: coarse 11-bit threshold search + candidate-count check, rare exact fallback (fewer instructions per token-head pair)
# speedup vs baseline: 1.1801x; 1.0168x over previous
; __device__ void topk_unit(const Params& p, unsigned char* smem, int unit) {
;     ...
;     bool ca_[2], cb_[2];
;     int pa[2], pb[2], ncand[2];
;     const unsigned long long lt = (1ull << lane) - 1ull;
; #pragma unroll
;     for (int hf = 0; hf < 2; ++hf) {
;       const int c_ = cnt[hf][0] + cnt[hf][1] + cnt[hf][2] + cnt[hf][3];
;       const unsigned long long bm = __ballot(c_ == 15);
;       const int srcT = __ffsll((long long)bm) - 1;
;       const unsigned T0 = (unsigned)__shfl((int)mxk[hf], srcT);
;       ca_[hf] = ka[hf] >= T0;
;       cb_[hf] = kb[hf] >= T0;
;       const unsigned long long ba = __ballot(ca_[hf]), bb = __ballot(cb_[hf]);
;       const int na = __popcll(ba);
;       pa[hf] = __popcll(ba & lt);
;       pb[hf] = na + __popcll(bb & lt);
;       ncand[hf] = na + __popcll(bb);
;     }
; #pragma unroll
;     for (int hf = 0; hf < 2; ++hf) {
;       unsigned* Cs = Ms + hf * 96 + 64;
;       if (lane < 32) Cs[lane] = 0u;
;       if (ca_[hf]) Cs[pa[hf]] = ka[hf];
;       if (cb_[hf]) Cs[pb[hf]] = kb[hf];
;     }
;     unsigned my[2];
;     int rk2[2][4];
; #pragma unroll
;     for (int hf = 0; hf < 2; ++hf) {
;       my[hf] = Ms[hf * 96 + 64 + (lane & 31)];
; #pragma unroll
;       for (int e = 0; e < 4; ++e) rk2[hf][e] = 0;
;     }
; #pragma unroll
;     for (int j = 0; j < 8; ++j)
; #pragma unroll
;       for (int hf = 0; hf < 2; ++hf) {
;         u32x4 x = *(const u32x4*)(Ms + hf * 96 + 64 + j * 4);
; #pragma unroll
;         for (int e = 0; e < 4; ++e) rk2[hf][e] += (x[e] > my[hf]) ? 1 : 0;
;       }
; #pragma unroll
;     for (int hf = 0; hf < 2; ++hf) {
;       const int r_ = rk2[hf][0] + rk2[hf][1] + rk2[hf][2] + rk2[hf][3];
;       if (lane < ncand[hf] && r_ < 16) {
;         tops[hf * 16 + r_] = ord_dec(my[hf] & ~127u);
;         topi[hf * 16 + r_] = 127 - (int)(my[hf] & 127u);
;       }
;     }
.Ltk_stepD:
	s_nop 1
	v_cmp_ge_u32_e64 s[86:87], v2, s84
	v_cmp_ge_u32_e64 s[88:89], v3, s84
	v_cmp_ge_u32_e64 s[68:69], v4, s85
	v_cmp_ge_u32_e64 s[70:71], v5, s85
	s_nop 1
	s_bcnt1_i32_b64 s72, s[86:87]
	s_bcnt1_i32_b64 s73, s[68:69]
	s_bcnt1_i32_b64 s0, s[88:89]
	s_bcnt1_i32_b64 s1, s[70:71]
	s_add_i32 s0, s0, s72
	s_add_i32 s1, s1, s73
	s_max_u32 s0, s0, s1
	s_cmp_gt_u32 s0, 32
	s_cbranch_scc1 .Ltk_fine
	v_mbcnt_lo_u32_b32 v44, s86, 0
	v_mbcnt_lo_u32_b32 v45, s88, 0
	v_mbcnt_lo_u32_b32 v46, s68, 0
	v_mbcnt_lo_u32_b32 v47, s70, 0
	v_mbcnt_hi_u32_b32 v44, s87, v44
	v_mbcnt_hi_u32_b32 v45, s89, v45
	v_mbcnt_hi_u32_b32 v46, s69, v46
	v_mbcnt_hi_u32_b32 v47, s71, v47
	v_add_u32_e32 v45, s72, v45
	v_add_u32_e32 v47, s73, v47
	v_lshl_add_u32 v44, v44, 2, v101
	v_lshl_add_u32 v45, v45, 2, v101
	v_lshl_add_u32 v46, v46, 2, v101
	v_lshl_add_u32 v47, v47, 2, v101
	s_mov_b64 exec, s[14:15]
	ds_write_b32 v105, v63 offset:256
	ds_write_b32 v105, v63 offset:640
	s_mov_b64 exec, s[86:87]
	ds_write_b32 v44, v2 offset:256
	s_mov_b64 exec, s[88:89]
	ds_write_b32 v45, v3 offset:256
	s_mov_b64 exec, s[68:69]
	ds_write_b32 v46, v4 offset:640
	s_mov_b64 exec, s[70:71]
	ds_write_b32 v47, v5 offset:640
	s_mov_b64 exec, s[46:47]
	ds_read_b32 v48, v89 offset:256
	ds_read_b128 v[12:15], v79 offset:256
	ds_read_b128 v[16:19], v79 offset:272
	ds_read_b128 v[20:23], v79 offset:288
	ds_read_b128 v[24:27], v79 offset:304
	ds_read_b128 v[28:31], v79 offset:320
	ds_read_b128 v[32:35], v79 offset:336
	ds_read_b128 v[36:39], v79 offset:352
	ds_read_b128 v[40:43], v79 offset:368
	v_mov_b32_e32 v49, 0
	v_mov_b32_e32 v50, 0
	s_waitcnt lgkmcnt(0)
	v_cmp_gt_u32_e64 s[68:69], v12, v48
	v_cmp_gt_u32_e64 s[70:71], v13, v48
	v_cmp_gt_u32_e64 s[72:73], v14, v48
	v_cmp_gt_u32_e64 s[74:75], v15, v48
	v_addc_co_u32_e64 v49, s[76:77], 0, v49, s[68:69]
	v_addc_co_u32_e64 v50, s[76:77], 0, v50, s[70:71]
	v_addc_co_u32_e64 v49, s[76:77], 0, v49, s[72:73]
	v_addc_co_u32_e64 v50, s[76:77], 0, v50, s[74:75]
	v_cmp_gt_u32_e64 s[68:69], v16, v48
	v_cmp_gt_u32_e64 s[70:71], v17, v48
	v_cmp_gt_u32_e64 s[72:73], v18, v48
	v_cmp_gt_u32_e64 s[74:75], v19, v48
	v_addc_co_u32_e64 v49, s[76:77], 0, v49, s[68:69]
	v_addc_co_u32_e64 v50, s[76:77], 0, v50, s[70:71]
	v_addc_co_u32_e64 v49, s[76:77], 0, v49, s[72:73]
	v_addc_co_u32_e64 v50, s[76:77], 0, v50, s[74:75]
	v_cmp_gt_u32_e64 s[68:69], v20, v48
	v_cmp_gt_u32_e64 s[70:71], v21, v48
	v_cmp_gt_u32_e64 s[72:73], v22, v48
	v_cmp_gt_u32_e64 s[74:75], v23, v48
	v_addc_co_u32_e64 v49, s[76:77], 0, v49, s[68:69]
	v_addc_co_u32_e64 v50, s[76:77], 0, v50, s[70:71]
	v_addc_co_u32_e64 v49, s[76:77], 0, v49, s[72:73]
	v_addc_co_u32_e64 v50, s[76:77], 0, v50, s[74:75]
	v_cmp_gt_u32_e64 s[68:69], v24, v48
	v_cmp_gt_u32_e64 s[70:71], v25, v48
	v_cmp_gt_u32_e64 s[72:73], v26, v48
	v_cmp_gt_u32_e64 s[74:75], v27, v48
	v_addc_co_u32_e64 v49, s[76:77], 0, v49, s[68:69]
	v_addc_co_u32_e64 v50, s[76:77], 0, v50, s[70:71]
	v_addc_co_u32_e64 v49, s[76:77], 0, v49, s[72:73]
	v_addc_co_u32_e64 v50, s[76:77], 0, v50, s[74:75]
	v_cmp_gt_u32_e64 s[68:69], v28, v48
	v_cmp_gt_u32_e64 s[70:71], v29, v48
	v_cmp_gt_u32_e64 s[72:73], v30, v48
	v_cmp_gt_u32_e64 s[74:75], v31, v48
	v_addc_co_u32_e64 v49, s[76:77], 0, v49, s[68:69]
	v_addc_co_u32_e64 v50, s[76:77], 0, v50, s[70:71]
	v_addc_co_u32_e64 v49, s[76:77], 0, v49, s[72:73]
	v_addc_co_u32_e64 v50, s[76:77], 0, v50, s[74:75]
	v_cmp_gt_u32_e64 s[68:69], v32, v48
	v_cmp_gt_u32_e64 s[70:71], v33, v48
	v_cmp_gt_u32_e64 s[72:73], v34, v48
	v_cmp_gt_u32_e64 s[74:75], v35, v48
	v_addc_co_u32_e64 v49, s[76:77], 0, v49, s[68:69]
	v_addc_co_u32_e64 v50, s[76:77], 0, v50, s[70:71]
	v_addc_co_u32_e64 v49, s[76:77], 0, v49, s[72:73]
	v_addc_co_u32_e64 v50, s[76:77], 0, v50, s[74:75]
	v_cmp_gt_u32_e64 s[68:69], v36, v48
	v_cmp_gt_u32_e64 s[70:71], v37, v48
	v_cmp_gt_u32_e64 s[72:73], v38, v48
	v_cmp_gt_u32_e64 s[74:75], v39, v48
	v_addc_co_u32_e64 v49, s[76:77], 0, v49, s[68:69]
	v_addc_co_u32_e64 v50, s[76:77], 0, v50, s[70:71]
	v_addc_co_u32_e64 v49, s[76:77], 0, v49, s[72:73]
	v_addc_co_u32_e64 v50, s[76:77], 0, v50, s[74:75]
	v_cmp_gt_u32_e64 s[68:69], v40, v48
	v_cmp_gt_u32_e64 s[70:71], v41, v48
	v_cmp_gt_u32_e64 s[72:73], v42, v48
	v_cmp_gt_u32_e64 s[74:75], v43, v48
	v_addc_co_u32_e64 v49, s[76:77], 0, v49, s[68:69]
	v_addc_co_u32_e64 v50, s[76:77], 0, v50, s[70:71]
	v_addc_co_u32_e64 v49, s[76:77], 0, v49, s[72:73]
	v_addc_co_u32_e64 v50, s[76:77], 0, v50, s[74:75]
	v_add_u32_e32 v49, v49, v50
	v_and_b32_e32 v51, 0xffffff80, v48
	v_cmp_gt_u32_e64 s[74:75], 16, v49
	v_ashrrev_i32_e32 v52, 31, v51
	v_and_b32_e32 v53, 0x7f, v48
	v_not_b32_e32 v52, v52
	v_sub_u32_e32 v53, 0x7f, v53
	v_or_b32_e32 v52, 0x80000000, v52
	v_lshl_add_u32 v54, v49, 2, v94
	v_xor_b32_e32 v51, v51, v52
	s_mov_b64 exec, s[74:75]
	ds_write_b32 v54, v51
	ds_write_b32 v54, v53 offset:128
	s_mov_b64 exec, s[46:47]
	ds_read_b32 v121, v113
	ds_read_b32 v122, v112 offset:64
	ds_read2_b32 v[124:125], v99 offset1:16
	ds_read_b32 v126, v113 offset:128
	ds_read_b32 v127, v112 offset:192
	s_waitcnt lgkmcnt(3)
	v_add_f32_e32 v128, v121, v122
	v_mov_b32_e32 v130, 0
	v_ashrrev_i32_e32 v129, 31, v128
	v_mov_b32_e32 v131, 0
	v_or_b32_e32 v129, 0x80000000, v129
	v_xor_b32_e32 v129, v128, v129
	v_and_or_b32 v129, v129, s3, v92
	v_cndmask_b32_e64 v129, 0, v129, s[4:5]
	ds_write_b32 v104, v129
	ds_read_b128 v[12:15], v101
	ds_read_b128 v[16:19], v101 offset:16
	ds_read_b128 v[20:23], v101 offset:32
	ds_read_b128 v[24:27], v101 offset:48
	ds_read_b128 v[28:31], v101 offset:64
	ds_read_b128 v[32:35], v101 offset:80
	ds_read_b128 v[36:39], v101 offset:96
	ds_read_b128 v[40:43], v101 offset:112
	s_waitcnt lgkmcnt(4)
; __device__ void topk_unit(const Params& p, unsigned char* smem, int unit) {
;     ...
;     float cs = 0.f;
;     unsigned ck = 0u;
;     if (lane < 50) {
;       cs = tops[ca] + tops[16 + cbb];
;       ck = (ord_key(cs) & ~255u) | (unsigned)(255 - (ca * 16 + cbb));
;     }
;     int rkA = 0, rkB = 0;
; #pragma unroll
;     for (int j = 0; j < 50; j += 2) {
;       const unsigned oj = (unsigned)__builtin_amdgcn_readlane((int)ck, j);
;       const unsigned oj2 = (unsigned)__builtin_amdgcn_readlane((int)ck, j + 1);
;       rkA += (oj > ck) ? 1 : 0;
;       rkB += (oj2 > ck) ? 1 : 0;
;     }
;     const int rk = rkA + rkB;
;     const float mx = tops[0] + tops[16];
;     const bool sel = (lane < 50) && (rk < 16);
;     const float ev = sel ? __expf(cs - mx) : 0.f;
;     const float sum = wave_sum(ev);
;     if (sel) {
;       const size_t o = (size_t)(tok0 + tk) * 128 + h * 16 + rk;
;       idxo[o] = topi[ca] * 128 + topi[16 + cbb];
;       go[o] = ev * __builtin_amdgcn_rcpf(sum);
;     }
	v_cmp_gt_u32_e64 s[68:69], v12, v129
	v_cmp_gt_u32_e64 s[70:71], v13, v129
	v_cmp_gt_u32_e64 s[72:73], v14, v129
	v_cmp_gt_u32_e64 s[74:75], v15, v129
	v_addc_co_u32_e64 v130, s[76:77], 0, v130, s[68:69]
	v_addc_co_u32_e64 v131, s[76:77], 0, v131, s[70:71]
	v_addc_co_u32_e64 v130, s[76:77], 0, v130, s[72:73]
	v_addc_co_u32_e64 v131, s[76:77], 0, v131, s[74:75]
	v_cmp_gt_u32_e64 s[68:69], v16, v129
	v_cmp_gt_u32_e64 s[70:71], v17, v129
	v_cmp_gt_u32_e64 s[72:73], v18, v129
	v_cmp_gt_u32_e64 s[74:75], v19, v129
	v_addc_co_u32_e64 v130, s[76:77], 0, v130, s[68:69]
	v_addc_co_u32_e64 v131, s[76:77], 0, v131, s[70:71]
	v_addc_co_u32_e64 v130, s[76:77], 0, v130, s[72:73]
	v_addc_co_u32_e64 v131, s[76:77], 0, v131, s[74:75]
	v_cmp_gt_u32_e64 s[68:69], v20, v129
	v_cmp_gt_u32_e64 s[70:71], v21, v129
	v_cmp_gt_u32_e64 s[72:73], v22, v129
	v_cmp_gt_u32_e64 s[74:75], v23, v129
	v_addc_co_u32_e64 v130, s[76:77], 0, v130, s[68:69]
	v_addc_co_u32_e64 v131, s[76:77], 0, v131, s[70:71]
	v_addc_co_u32_e64 v130, s[76:77], 0, v130, s[72:73]
	v_addc_co_u32_e64 v131, s[76:77], 0, v131, s[74:75]
	v_cmp_gt_u32_e64 s[68:69], v24, v129
	v_cmp_gt_u32_e64 s[70:71], v25, v129
	v_cmp_gt_u32_e64 s[72:73], v26, v129
	v_cmp_gt_u32_e64 s[74:75], v27, v129
	v_addc_co_u32_e64 v130, s[76:77], 0, v130, s[68:69]
	v_addc_co_u32_e64 v131, s[76:77], 0, v131, s[70:71]
	v_addc_co_u32_e64 v130, s[76:77], 0, v130, s[72:73]
	v_addc_co_u32_e64 v131, s[76:77], 0, v131, s[74:75]
	ds_read_b128 v[12:15], v101 offset:128
	ds_read_b128 v[16:19], v101 offset:144
	ds_read_b128 v[20:23], v101 offset:160
	ds_read_b128 v[24:27], v101 offset:176
	ds_read_b128 v[148:151], v101 offset:192
	s_waitcnt lgkmcnt(5)
	v_cmp_gt_u32_e64 s[68:69], v28, v129
	v_cmp_gt_u32_e64 s[70:71], v29, v129
	v_cmp_gt_u32_e64 s[72:73], v30, v129
	v_cmp_gt_u32_e64 s[74:75], v31, v129
	v_addc_co_u32_e64 v130, s[76:77], 0, v130, s[68:69]
	v_addc_co_u32_e64 v131, s[76:77], 0, v131, s[70:71]
	v_addc_co_u32_e64 v130, s[76:77], 0, v130, s[72:73]
	v_addc_co_u32_e64 v131, s[76:77], 0, v131, s[74:75]
	v_cmp_gt_u32_e64 s[68:69], v32, v129
	v_cmp_gt_u32_e64 s[70:71], v33, v129
	v_cmp_gt_u32_e64 s[72:73], v34, v129
	v_cmp_gt_u32_e64 s[74:75], v35, v129
	v_addc_co_u32_e64 v130, s[76:77], 0, v130, s[68:69]
	v_addc_co_u32_e64 v131, s[76:77], 0, v131, s[70:71]
	v_addc_co_u32_e64 v130, s[76:77], 0, v130, s[72:73]
	v_addc_co_u32_e64 v131, s[76:77], 0, v131, s[74:75]
	v_cmp_gt_u32_e64 s[68:69], v36, v129
	v_cmp_gt_u32_e64 s[70:71], v37, v129
	v_cmp_gt_u32_e64 s[72:73], v38, v129
	v_cmp_gt_u32_e64 s[74:75], v39, v129
	v_addc_co_u32_e64 v130, s[76:77], 0, v130, s[68:69]
	v_addc_co_u32_e64 v131, s[76:77], 0, v131, s[70:71]
	v_addc_co_u32_e64 v130, s[76:77], 0, v130, s[72:73]
	v_addc_co_u32_e64 v131, s[76:77], 0, v131, s[74:75]
	v_cmp_gt_u32_e64 s[68:69], v40, v129
	v_cmp_gt_u32_e64 s[70:71], v41, v129
	v_cmp_gt_u32_e64 s[72:73], v42, v129
	v_cmp_gt_u32_e64 s[74:75], v43, v129
	v_addc_co_u32_e64 v130, s[76:77], 0, v130, s[68:69]
	v_addc_co_u32_e64 v131, s[76:77], 0, v131, s[70:71]
	v_addc_co_u32_e64 v130, s[76:77], 0, v130, s[72:73]
	v_addc_co_u32_e64 v131, s[76:77], 0, v131, s[74:75]
	s_waitcnt lgkmcnt(0)
	v_cmp_gt_u32_e64 s[68:69], v12, v129
	v_cmp_gt_u32_e64 s[70:71], v13, v129
	v_cmp_gt_u32_e64 s[72:73], v14, v129
	v_cmp_gt_u32_e64 s[74:75], v15, v129
	v_addc_co_u32_e64 v130, s[76:77], 0, v130, s[68:69]
	v_addc_co_u32_e64 v131, s[76:77], 0, v131, s[70:71]
	v_addc_co_u32_e64 v130, s[76:77], 0, v130, s[72:73]
	v_addc_co_u32_e64 v131, s[76:77], 0, v131, s[74:75]
	v_cmp_gt_u32_e64 s[68:69], v16, v129
	v_cmp_gt_u32_e64 s[70:71], v17, v129
	v_cmp_gt_u32_e64 s[72:73], v18, v129
	v_cmp_gt_u32_e64 s[74:75], v19, v129
	v_addc_co_u32_e64 v130, s[76:77], 0, v130, s[68:69]
	v_addc_co_u32_e64 v131, s[76:77], 0, v131, s[70:71]
	v_addc_co_u32_e64 v130, s[76:77], 0, v130, s[72:73]
	v_addc_co_u32_e64 v131, s[76:77], 0, v131, s[74:75]
	v_cmp_gt_u32_e64 s[68:69], v20, v129
	v_cmp_gt_u32_e64 s[70:71], v21, v129
	v_cmp_gt_u32_e64 s[72:73], v22, v129
	v_cmp_gt_u32_e64 s[74:75], v23, v129
	v_addc_co_u32_e64 v130, s[76:77], 0, v130, s[68:69]
	v_addc_co_u32_e64 v131, s[76:77], 0, v131, s[70:71]
	v_addc_co_u32_e64 v130, s[76:77], 0, v130, s[72:73]
	v_addc_co_u32_e64 v131, s[76:77], 0, v131, s[74:75]
	v_cmp_gt_u32_e64 s[68:69], v24, v129
	v_cmp_gt_u32_e64 s[70:71], v25, v129
	v_cmp_gt_u32_e64 s[72:73], v26, v129
	v_cmp_gt_u32_e64 s[74:75], v27, v129
	v_addc_co_u32_e64 v130, s[76:77], 0, v130, s[68:69]
	v_addc_co_u32_e64 v131, s[76:77], 0, v131, s[70:71]
	v_addc_co_u32_e64 v130, s[76:77], 0, v130, s[72:73]
	v_addc_co_u32_e64 v131, s[76:77], 0, v131, s[74:75]
	v_cmp_gt_u32_e64 s[68:69], v148, v129
	v_cmp_gt_u32_e64 s[70:71], v149, v129
	v_cmp_gt_u32_e64 s[72:73], v150, v129
	v_cmp_gt_u32_e64 s[74:75], v151, v129
	v_addc_co_u32_e64 v130, s[76:77], 0, v130, s[68:69]
	v_addc_co_u32_e64 v131, s[76:77], 0, v131, s[70:71]
	v_addc_co_u32_e64 v130, s[76:77], 0, v130, s[72:73]
	v_addc_co_u32_e64 v131, s[76:77], 0, v131, s[74:75]
	v_add_u32_e32 v130, v130, v131
	v_mov_b32_e32 v131, 0
	v_cmp_gt_u32_e64 s[78:79], 16, v130
	v_add_f32_e32 v132, v124, v125
	v_sub_f32_e32 v132, v128, v132
	s_and_b64 s[78:79], s[78:79], s[4:5]
	v_mul_f32_e32 v132, 0x3fb8aa3b, v132
	v_exp_f32_e32 v132, v132
	v_lshl_add_u32 v136, v126, 7, v127
	v_lshl_add_u64 v[140:141], v[90:91], 0, v[130:131]
	v_cndmask_b32_e64 v132, 0, v132, s[78:79]
	v_lshlrev_b64 v[140:141], 2, v[140:141]
	s_nop 0
	v_add_f32_dpp v133, v132, v132 quad_perm:[1,0,3,2] row_mask:0xf bank_mask:0xf
	v_lshl_add_u64 v[142:143], s[38:39], 0, v[140:141]
	v_lshl_add_u64 v[144:145], s[40:41], 0, v[140:141]
	v_add_f32_dpp v133, v133, v133 quad_perm:[2,3,0,1] row_mask:0xf bank_mask:0xf
	s_nop 1
	v_add_f32_dpp v133, v133, v133 row_half_mirror row_mask:0xf bank_mask:0xf
	s_nop 1
	v_add_f32_dpp v133, v133, v133 row_mirror row_mask:0xf bank_mask:0xf
	s_nop 1
	v_readlane_b32 s80, v133, 0
	v_readlane_b32 s81, v133, 16
	v_readlane_b32 s82, v133, 32
	v_readlane_b32 s83, v133, 48
	v_mov_b32_e32 v134, s80
	s_nop 0
	v_add_f32_e32 v134, s81, v134
	v_add_f32_e32 v134, s82, v134
	v_add_f32_e32 v134, s83, v134
	v_rcp_f32_e32 v134, v134
	s_nop 0
	v_mul_f32_e32 v135, v132, v134
	s_mov_b64 exec, s[78:79]
	global_store_dword v[142:143], v136, off
	global_store_dword v[144:145], v135, off
	s_mov_b64 exec, s[46:47]
	s_addk_i32 s12, 0x410
	v_lshl_add_u64 v[90:91], v[90:91], 0, s[44:45]
	s_cmpk_lg_i32 s12, 0x4100
	s_cbranch_scc1 .Ltk2_loop
	s_branch .LBB0_1109
; __device__ void topk_unit(const Params& p, unsigned char* smem, int unit) {
;     ...
;     for (int hf = 0; hf < 2; ++hf) {
;       const int c_ = cnt[hf][0] + cnt[hf][1] + cnt[hf][2] + cnt[hf][3];
;       const unsigned long long bm = __ballot(c_ == 15);
;       const int srcT = __ffsll((long long)bm) - 1;
;       const unsigned T0 = (unsigned)__shfl((int)mxk[hf], srcT);
.Ltk_fine:
	s_or_b32 s86, s84, 0x100000
	s_or_b32 s87, s85, 0x100000
	v_cmp_ge_u32_e64 s[68:69], v6, s86
	v_cmp_ge_u32_e64 s[70:71], v7, s87
	s_bcnt1_i32_b64 s72, s[68:69]
	s_bcnt1_i32_b64 s73, s[70:71]
	s_cmp_ge_u32 s72, 16
	s_cselect_b32 s84, s86, s84
	s_cmp_ge_u32 s73, 16
	s_cselect_b32 s85, s87, s85
	s_or_b32 s86, s84, 0x80000
	s_or_b32 s87, s85, 0x80000
	v_cmp_ge_u32_e64 s[68:69], v6, s86
	v_cmp_ge_u32_e64 s[70:71], v7, s87
	s_bcnt1_i32_b64 s72, s[68:69]
	s_bcnt1_i32_b64 s73, s[70:71]
	s_cmp_ge_u32 s72, 16
	s_cselect_b32 s84, s86, s84
	s_cmp_ge_u32 s73, 16
	s_cselect_b32 s85, s87, s85
	s_or_b32 s86, s84, 0x40000
	s_or_b32 s87, s85, 0x40000
	v_cmp_ge_u32_e64 s[68:69], v6, s86
	v_cmp_ge_u32_e64 s[70:71], v7, s87
	s_bcnt1_i32_b64 s72, s[68:69]
	s_bcnt1_i32_b64 s73, s[70:71]
	s_cmp_ge_u32 s72, 16
	s_cselect_b32 s84, s86, s84
	s_cmp_ge_u32 s73, 16
	s_cselect_b32 s85, s87, s85
	s_or_b32 s86, s84, 0x20000
	s_or_b32 s87, s85, 0x20000
	v_cmp_ge_u32_e64 s[68:69], v6, s86
	v_cmp_ge_u32_e64 s[70:71], v7, s87
	s_bcnt1_i32_b64 s72, s[68:69]
	s_bcnt1_i32_b64 s73, s[70:71]
	s_cmp_ge_u32 s72, 16
	s_cselect_b32 s84, s86, s84
	s_cmp_ge_u32 s73, 16
	s_cselect_b32 s85, s87, s85
	s_or_b32 s86, s84, 0x10000
	s_or_b32 s87, s85, 0x10000
	v_cmp_ge_u32_e64 s[68:69], v6, s86
	v_cmp_ge_u32_e64 s[70:71], v7, s87
	s_bcnt1_i32_b64 s72, s[68:69]
	s_bcnt1_i32_b64 s73, s[70:71]
	s_cmp_ge_u32 s72, 16
	s_cselect_b32 s84, s86, s84
	s_cmp_ge_u32 s73, 16
	s_cselect_b32 s85, s87, s85
	s_or_b32 s86, s84, 0x8000
	s_or_b32 s87, s85, 0x8000
	v_cmp_ge_u32_e64 s[68:69], v6, s86
	v_cmp_ge_u32_e64 s[70:71], v7, s87
	s_bcnt1_i32_b64 s72, s[68:69]
	s_bcnt1_i32_b64 s73, s[70:71]
	s_cmp_ge_u32 s72, 16
	s_cselect_b32 s84, s86, s84
	s_cmp_ge_u32 s73, 16
	s_cselect_b32 s85, s87, s85
	s_or_b32 s86, s84, 0x4000
	s_or_b32 s87, s85, 0x4000
	v_cmp_ge_u32_e64 s[68:69], v6, s86
	v_cmp_ge_u32_e64 s[70:71], v7, s87
	s_bcnt1_i32_b64 s72, s[68:69]
	s_bcnt1_i32_b64 s73, s[70:71]
	s_cmp_ge_u32 s72, 16
	s_cselect_b32 s84, s86, s84
	s_cmp_ge_u32 s73, 16
	s_cselect_b32 s85, s87, s85
	s_or_b32 s86, s84, 0x2000
	s_or_b32 s87, s85, 0x2000
	v_cmp_ge_u32_e64 s[68:69], v6, s86
	v_cmp_ge_u32_e64 s[70:71], v7, s87
	s_bcnt1_i32_b64 s72, s[68:69]
	s_bcnt1_i32_b64 s73, s[70:71]
	s_cmp_ge_u32 s72, 16
	s_cselect_b32 s84, s86, s84
	s_cmp_ge_u32 s73, 16
	s_cselect_b32 s85, s87, s85
	s_or_b32 s86, s84, 0x1000
	s_or_b32 s87, s85, 0x1000
	v_cmp_ge_u32_e64 s[68:69], v6, s86
	v_cmp_ge_u32_e64 s[70:71], v7, s87
	s_bcnt1_i32_b64 s72, s[68:69]
	s_bcnt1_i32_b64 s73, s[70:71]
	s_cmp_ge_u32 s72, 16
	s_cselect_b32 s84, s86, s84
	s_cmp_ge_u32 s73, 16
	s_cselect_b32 s85, s87, s85
	s_or_b32 s86, s84, 0x800
	s_or_b32 s87, s85, 0x800
	v_cmp_ge_u32_e64 s[68:69], v6, s86
	v_cmp_ge_u32_e64 s[70:71], v7, s87
	s_bcnt1_i32_b64 s72, s[68:69]
	s_bcnt1_i32_b64 s73, s[70:71]
	s_cmp_ge_u32 s72, 16
	s_cselect_b32 s84, s86, s84
	s_cmp_ge_u32 s73, 16
	s_cselect_b32 s85, s87, s85
	s_or_b32 s86, s84, 0x400
	s_or_b32 s87, s85, 0x400
	v_cmp_ge_u32_e64 s[68:69], v6, s86
	v_cmp_ge_u32_e64 s[70:71], v7, s87
	s_bcnt1_i32_b64 s72, s[68:69]
	s_bcnt1_i32_b64 s73, s[70:71]
	s_cmp_ge_u32 s72, 16
	s_cselect_b32 s84, s86, s84
	s_cmp_ge_u32 s73, 16
	s_cselect_b32 s85, s87, s85
	s_or_b32 s86, s84, 0x200
	s_or_b32 s87, s85, 0x200
	v_cmp_ge_u32_e64 s[68:69], v6, s86
	v_cmp_ge_u32_e64 s[70:71], v7, s87
	s_bcnt1_i32_b64 s72, s[68:69]
	s_bcnt1_i32_b64 s73, s[70:71]
	s_cmp_ge_u32 s72, 16
	s_cselect_b32 s84, s86, s84
	s_cmp_ge_u32 s73, 16
	s_cselect_b32 s85, s87, s85
	s_or_b32 s86, s84, 0x100
	s_or_b32 s87, s85, 0x100
	v_cmp_ge_u32_e64 s[68:69], v6, s86
	v_cmp_ge_u32_e64 s[70:71], v7, s87
	s_bcnt1_i32_b64 s72, s[68:69]
	s_bcnt1_i32_b64 s73, s[70:71]
	s_cmp_ge_u32 s72, 16
	s_cselect_b32 s84, s86, s84
	s_cmp_ge_u32 s73, 16
	s_cselect_b32 s85, s87, s85
	s_or_b32 s86, s84, 0x80
	s_or_b32 s87, s85, 0x80
	v_cmp_ge_u32_e64 s[68:69], v6, s86
	v_cmp_ge_u32_e64 s[70:71], v7, s87
	s_bcnt1_i32_b64 s72, s[68:69]
	s_bcnt1_i32_b64 s73, s[70:71]
	s_cmp_ge_u32 s72, 16
	s_cselect_b32 s84, s86, s84
	s_cmp_ge_u32 s73, 16
	s_cselect_b32 s85, s87, s85
	s_or_b32 s86, s84, 64
	s_or_b32 s87, s85, 64
	v_cmp_ge_u32_e64 s[68:69], v6, s86
	v_cmp_ge_u32_e64 s[70:71], v7, s87
	s_bcnt1_i32_b64 s72, s[68:69]
	s_bcnt1_i32_b64 s73, s[70:71]
	s_cmp_ge_u32 s72, 16
	s_cselect_b32 s84, s86, s84
	s_cmp_ge_u32 s73, 16
	s_cselect_b32 s85, s87, s85
	s_or_b32 s86, s84, 32
	s_or_b32 s87, s85, 32
	v_cmp_ge_u32_e64 s[68:69], v6, s86
	v_cmp_ge_u32_e64 s[70:71], v7, s87
	s_bcnt1_i32_b64 s72, s[68:69]
	s_bcnt1_i32_b64 s73, s[70:71]
	s_cmp_ge_u32 s72, 16
	s_cselect_b32 s84, s86, s84
	s_cmp_ge_u32 s73, 16
	s_cselect_b32 s85, s87, s85
	s_or_b32 s86, s84, 16
	s_or_b32 s87, s85, 16
	v_cmp_ge_u32_e64 s[68:69], v6, s86
	v_cmp_ge_u32_e64 s[70:71], v7, s87
	s_bcnt1_i32_b64 s72, s[68:69]
	s_bcnt1_i32_b64 s73, s[70:71]
	s_cmp_ge_u32 s72, 16
	s_cselect_b32 s84, s86, s84
	s_cmp_ge_u32 s73, 16
	s_cselect_b32 s85, s87, s85
	s_or_b32 s86, s84, 8
	s_or_b32 s87, s85, 8
	v_cmp_ge_u32_e64 s[68:69], v6, s86
	v_cmp_ge_u32_e64 s[70:71], v7, s87
	s_bcnt1_i32_b64 s72, s[68:69]
	s_bcnt1_i32_b64 s73, s[70:71]
	s_cmp_ge_u32 s72, 16
	s_cselect_b32 s84, s86, s84
	s_cmp_ge_u32 s73, 16
	s_cselect_b32 s85, s87, s85
	s_or_b32 s86, s84, 4
	s_or_b32 s87, s85, 4
	v_cmp_ge_u32_e64 s[68:69], v6, s86
	v_cmp_ge_u32_e64 s[70:71], v7, s87
	s_bcnt1_i32_b64 s72, s[68:69]
	s_bcnt1_i32_b64 s73, s[70:71]
	s_cmp_ge_u32 s72, 16
	s_cselect_b32 s84, s86, s84
	s_cmp_ge_u32 s73, 16
	s_cselect_b32 s85, s87, s85
	s_or_b32 s86, s84, 2
	s_or_b32 s87, s85, 2
	v_cmp_ge_u32_e64 s[68:69], v6, s86
	v_cmp_ge_u32_e64 s[70:71], v7, s87
	s_bcnt1_i32_b64 s72, s[68:69]
	s_bcnt1_i32_b64 s73, s[70:71]
	s_cmp_ge_u32 s72, 16
	s_cselect_b32 s84, s86, s84
	s_cmp_ge_u32 s73, 16
	s_cselect_b32 s85, s87, s85
	s_or_b32 s86, s84, 1
	s_or_b32 s87, s85, 1
	v_cmp_ge_u32_e64 s[68:69], v6, s86
	v_cmp_ge_u32_e64 s[70:71], v7, s87
	s_bcnt1_i32_b64 s72, s[68:69]
	s_bcnt1_i32_b64 s73, s[70:71]
	s_cmp_ge_u32 s72, 16
	s_cselect_b32 s84, s86, s84
	s_cmp_ge_u32 s73, 16
	s_cselect_b32 s85, s87, s85
	s_branch .Ltk_stepD
